# retention per-step K/V prefetch: addresses as one scalar 64-bit base per step plus a 24-bit multiply-add per-lane offset (saddr loads), replacing ~70 vector address ops
# speedup vs baseline: 1.0017x; 1.0017x over previous
.LBB0_117:
	s_waitcnt vmcnt(12)
	v_cvt_pk_bf16_f32 v104, v100, v101
	v_cvt_pk_bf16_f32 v105, v102, v103
	v_cvt_pk_bf16_f32 v106, v96, v97
	v_cvt_pk_bf16_f32 v107, v98, v99
	ds_write2_b64 v215, v[104:105], v[106:107] offset1:4
	v_cvt_pk_bf16_f32 v104, v92, v93
	v_cvt_pk_bf16_f32 v105, v94, v95
	v_cvt_pk_bf16_f32 v106, v88, v89
	v_cvt_pk_bf16_f32 v107, v90, v91
	ds_write2_b64 v215, v[104:105], v[106:107] offset0:8 offset1:12
	v_cvt_pk_bf16_f32 v104, v84, v85
	v_cvt_pk_bf16_f32 v105, v86, v87
	v_cvt_pk_bf16_f32 v106, v80, v81
	v_cvt_pk_bf16_f32 v107, v82, v83
	ds_write2_b64 v216, v[104:105], v[106:107] offset0:160 offset1:164
	v_cvt_pk_bf16_f32 v104, v76, v77
	v_cvt_pk_bf16_f32 v105, v78, v79
	v_cvt_pk_bf16_f32 v106, v72, v73
	v_cvt_pk_bf16_f32 v107, v74, v75
	ds_write2_b64 v216, v[104:105], v[106:107] offset0:168 offset1:172
	ds_write_b128 v217, v[0:3]
	ds_write_b128 v218, v[4:7]
	ds_write_b128 v219, v[8:11]
	ds_write_b128 v220, v[12:15]
	ds_write_b128 v221, v[28:31]
	ds_write_b128 v222, v[44:47]
	ds_write_b128 v223, v[56:59]
	ds_write_b128 v224, v[60:63]
	ds_write_b128 v225, v[64:67]
	v_lshlrev_b32_e32 v104, 16, v64
	v_and_b32_e32 v105, 0xffff0000, v64
	v_mul_f32_e32 v104, v246, v104
	v_mul_f32_e32 v105, v246, v105
	v_cvt_pk_bf16_f32 v104, v104, v105
	v_lshlrev_b32_e32 v105, 16, v65
	v_and_b32_e32 v106, 0xffff0000, v65
	v_mul_f32_e32 v105, v246, v105
	v_mul_f32_e32 v106, v246, v106
	v_cvt_pk_bf16_f32 v105, v105, v106
	v_lshlrev_b32_e32 v106, 16, v66
	v_and_b32_e32 v107, 0xffff0000, v66
	v_mul_f32_e32 v106, v246, v106
	v_mul_f32_e32 v107, v246, v107
	v_cvt_pk_bf16_f32 v106, v106, v107
	v_lshlrev_b32_e32 v107, 16, v67
	v_mul_f32_e32 v107, v246, v107
	v_and_b32_e32 v108, 0xffff0000, v67
	v_mul_f32_e32 v108, v246, v108
	v_cvt_pk_bf16_f32 v107, v107, v108
	ds_write_b128 v226, v[104:107]
	ds_write_b128 v227, v[68:71]
	v_lshlrev_b32_e32 v104, 16, v68
	v_and_b32_e32 v105, 0xffff0000, v68
	v_mul_f32_e32 v104, v247, v104
	v_mul_f32_e32 v105, v247, v105
	v_cvt_pk_bf16_f32 v104, v104, v105
	v_lshlrev_b32_e32 v105, 16, v69
	v_and_b32_e32 v106, 0xffff0000, v69
	v_mul_f32_e32 v105, v247, v105
	v_mul_f32_e32 v106, v247, v106
	v_cvt_pk_bf16_f32 v105, v105, v106
	v_lshlrev_b32_e32 v106, 16, v70
	v_and_b32_e32 v107, 0xffff0000, v70
	s_add_i32 s51, s52, 1
	v_mul_f32_e32 v106, v247, v106
	v_mul_f32_e32 v107, v247, v107
	s_cmp_ge_u32 s51, s45
	v_cvt_pk_bf16_f32 v106, v106, v107
	v_lshlrev_b32_e32 v107, 16, v71
	s_cselect_b64 s[12:13], -1, 0
	s_cmp_lt_u32 s51, s45
	v_mul_f32_e32 v107, v247, v107
	v_and_b32_e32 v108, 0xffff0000, v71
	s_cselect_b64 s[14:15], -1, 0
	s_and_b64 vcc, exec, s[12:13]
	v_mul_f32_e32 v108, v247, v108
	v_cvt_pk_bf16_f32 v107, v107, v108
	ds_write_b128 v228, v[104:107]
	s_waitcnt lgkmcnt(0)
	s_barrier
	s_cbranch_vccnz .Lret_last
	s_sub_i32 s11, s49, s51
	s_and_b64 s[34:35], s[0:1], exec
	s_cselect_b32 s11, s51, s11
	s_lshl_b32 s11, s11, 7
	s_add_i32 s53, s11, s48
	s_mul_hi_i32 s55, s53, s69
	s_mul_i32 s54, s53, s69
	v_mad_u32_u24 v120, v236, s69, v144
	v_mad_u32_u24 v121, v237, s69, v144
	s_add_u32 s54, s54, s42
	s_addc_u32 s55, s55, s43
	v_mad_u32_u24 v122, v238, s69, v144
	v_mad_u32_u24 v123, v239, s69, v144
	s_add_u32 s34, s46, s68
	s_addc_u32 s35, 0, 0
	v_mad_u32_u24 v124, v240, s69, v144
	v_mad_u32_u24 v125, v241, s69, v144
	s_add_u32 s34, s34, s54
	s_addc_u32 s35, s35, s55
	v_mad_u32_u24 v126, v242, s69, v144
	v_mad_u32_u24 v127, v243, s69, v144
	s_add_u32 s100, s46, s10
	s_addc_u32 s101, 0, 0
	v_mad_u32_u24 v128, v244, s69, v156
	v_mad_u32_u24 v129, v245, s69, v156
	s_add_u32 s100, s100, 0x2000
	s_addc_u32 s101, s101, 0
	v_mov_b32_e32 v157, v145
	s_add_u32 s100, s100, s54
	s_addc_u32 s101, s101, s55
	global_load_dwordx4 v[0:3], v120, s[34:35]
	global_load_dwordx4 v[4:7], v121, s[34:35]
	global_load_dwordx4 v[8:11], v122, s[34:35]
	global_load_dwordx4 v[12:15], v123, s[34:35]
	global_load_dwordx4 v[28:31], v124, s[34:35]
	global_load_dwordx4 v[44:47], v125, s[34:35]
	global_load_dwordx4 v[56:59], v126, s[34:35]
	global_load_dwordx4 v[60:63], v127, s[34:35]
	global_load_dwordx4 v[64:67], v128, s[100:101] nt
	global_load_dwordx4 v[68:71], v129, s[100:101] nt
	s_waitcnt vmcnt(10)
	s_branch .LBB0_119
